# SSD chunk staging: raw B copies issued behind the first barrier and the four dt/decay lane gathers issued together
# speedup vs baseline: 1.0663x; 1.0010x over previous
.LBB0_1861:
	s_or_b64 exec, exec, s[88:89]
	v_mul_f32_e64 v1, v212, -v0
	s_waitcnt lgkmcnt(0)
	s_barrier
	ds_write_b128 v241, v[16:19]
	ds_write_b128 v242, v[20:23]
	ds_write_b128 v243, v[24:27]
	ds_write_b128 v244, v[28:31]
	v_add_f32_dpp v1, v1, v1 row_shr:1 row_mask:0xf bank_mask:0xf
	s_nop 1
	v_add_f32_dpp v1, v1, v1 row_shr:2 row_mask:0xf bank_mask:0xf
	s_nop 1
	v_add_f32_dpp v1, v1, v1 row_shr:4 row_mask:0xf bank_mask:0xf
	s_nop 1
	v_add_f32_dpp v1, v1, v1 row_shr:8 row_mask:0xf bank_mask:0xf
	s_nop 1
	v_add_f32_dpp v1, v1, v1 row_bcast:15 row_mask:0xa bank_mask:0xf
	s_nop 1
	v_add_f32_dpp v1, v1, v1 row_bcast:31 row_mask:0xc bank_mask:0xf
	v_mul_f32_e32 v2, 0x3fb8aa3b, v1
	v_exp_f32_e32 v3, v2
	v_readlane_b32 s98, v1, 63
	v_readlane_b32 s99, v3, 63
	s_and_saveexec_b64 s[58:59], s[80:81]
	ds_write2st64_b32 v222, v1, v3 offset0:192 offset1:195
	s_or_b64 exec, exec, s[58:59]
	v_mov_b32_e32 v6, s99
	v_sub_f32_e32 v1, s98, v1
	v_mul_f32_e32 v1, 0x3fb8aa3b, v1
	v_exp_f32_e32 v1, v1
	ds_bpermute_b32 v2, v223, v0
	ds_bpermute_b32 v230, v224, v0
	v_lshlrev_b32_e32 v64, 16, v8
	v_and_b32_e32 v65, 0xffff0000, v8
	ds_bpermute_b32 v4, v223, v1
	ds_bpermute_b32 v232, v224, v1
	v_lshlrev_b32_e32 v66, 16, v9
	v_and_b32_e32 v67, 0xffff0000, v9
	v_lshlrev_b32_e32 v72, 16, v10
	v_and_b32_e32 v73, 0xffff0000, v10
	v_lshlrev_b32_e32 v76, 16, v11
	v_and_b32_e32 v77, 0xffff0000, v11
	s_waitcnt lgkmcnt(3)
	v_pk_mul_f32 v[64:65], v[2:3], v[64:65] op_sel_hi:[0,1]
	v_pk_mul_f32 v[66:67], v[2:3], v[66:67] op_sel_hi:[0,1]
	v_pk_mul_f32 v[72:73], v[2:3], v[72:73] op_sel_hi:[0,1]
	v_pk_mul_f32 v[2:3], v[2:3], v[76:77] op_sel_hi:[0,1]
	s_waitcnt lgkmcnt(1)
	v_pk_mul_f32 v[68:69], v[64:65], v[4:5] op_sel_hi:[1,0]
	v_pk_mul_f32 v[70:71], v[66:67], v[4:5] op_sel_hi:[1,0]
	v_pk_mul_f32 v[76:77], v[2:3], v[4:5] op_sel_hi:[1,0]
	v_cvt_pk_bf16_f32 v64, v64, v65
	v_cvt_pk_bf16_f32 v65, v66, v67
	v_cvt_pk_bf16_f32 v67, v2, v3
	v_pk_mul_f32 v[74:75], v[72:73], v[4:5] op_sel_hi:[1,0]
	v_cvt_pk_bf16_f32 v66, v72, v73
	ds_write_b128 v239, v[64:67] offset:32768
	v_cvt_pk_bf16_f32 v64, v68, v69
	v_cvt_pk_bf16_f32 v65, v70, v71
	v_cvt_pk_bf16_f32 v66, v74, v75
	v_cvt_pk_bf16_f32 v67, v76, v77
	ds_write_b128 v239, v[64:67] offset:40960
	v_lshlrev_b32_e32 v64, 16, v12
	v_and_b32_e32 v65, 0xffff0000, v12
	v_lshlrev_b32_e32 v68, 16, v13
	v_and_b32_e32 v69, 0xffff0000, v13
	v_lshlrev_b32_e32 v72, 16, v14
	v_and_b32_e32 v73, 0xffff0000, v14
	v_lshlrev_b32_e32 v76, 16, v15
	v_and_b32_e32 v77, 0xffff0000, v15
	s_waitcnt lgkmcnt(2)
	v_pk_mul_f32 v[64:65], v[230:231], v[64:65] op_sel_hi:[0,1]
	v_pk_mul_f32 v[68:69], v[230:231], v[68:69] op_sel_hi:[0,1]
	v_pk_mul_f32 v[72:73], v[230:231], v[72:73] op_sel_hi:[0,1]
	v_pk_mul_f32 v[76:77], v[230:231], v[76:77] op_sel_hi:[0,1]
	v_pk_mul_f32 v[66:67], v[64:65], v[232:233] op_sel_hi:[1,0]
	v_pk_mul_f32 v[70:71], v[68:69], v[232:233] op_sel_hi:[1,0]
	v_pk_mul_f32 v[74:75], v[72:73], v[232:233] op_sel_hi:[1,0]
	v_pk_mul_f32 v[78:79], v[76:77], v[232:233] op_sel_hi:[1,0]
	v_cvt_pk_bf16_f32 v0, v64, v65
	v_cvt_pk_bf16_f32 v1, v68, v69
	v_cvt_pk_bf16_f32 v2, v72, v73
	v_cvt_pk_bf16_f32 v3, v76, v77
	ds_write_b128 v240, v[0:3] offset:32768
	v_cvt_pk_bf16_f32 v0, v66, v67
	v_cvt_pk_bf16_f32 v1, v70, v71
	v_cvt_pk_bf16_f32 v2, v74, v75
	v_cvt_pk_bf16_f32 v3, v78, v79
	ds_write_b128 v240, v[0:3] offset:40960
	s_waitcnt lgkmcnt(0)
	s_barrier
	v_mov_b64_e32 v[64:65], v[84:85]
	v_mov_b64_e32 v[68:69], v[92:93]
	v_mov_b64_e32 v[72:73], v[88:89]
	v_mov_b64_e32 v[76:77], v[80:81]
	s_cmpk_eq_i32 s94, 0x1100
	v_mov_b64_e32 v[66:67], v[86:87]
	v_mov_b64_e32 v[70:71], v[94:95]
	v_mov_b64_e32 v[74:75], v[90:91]
	v_mov_b64_e32 v[78:79], v[82:83]
	s_cbranch_scc1 .LBB0_1875
	s_cmp_lt_u32 s95, 3
	s_cselect_b64 s[58:59], -1, 0
	s_cmp_gt_u32 s95, 2
	s_cselect_b64 s[88:89], -1, 0
	s_mov_b64 s[90:91], -1
	s_and_b64 vcc, exec, s[88:89]
	s_cbranch_vccz .LBB0_1870
	s_and_saveexec_b64 s[90:91], s[2:3]
	s_xor_b64 s[90:91], exec, s[90:91]
	s_sub_i32 s97, 0x1080, s96
	s_or_saveexec_b64 s[90:91], s[90:91]
	v_mov_b32_e32 v2, s97
	s_xor_b64 exec, exec, s[90:91]
	s_add_i32 s96, s94, 0xffffff00
	v_mov_b32_e32 v2, s96
	s_or_b64 exec, exec, s[90:91]
	s_mov_b64 s[90:91], 0
